# P3 RWKV loader waves run a private two-chunk-unrolled loop (same barrier and counters, one taken branch per chunk pair, no role dispatch or parity/range tests); last chunks fall back to the shared loo
# speedup vs baseline: 1.0094x; 1.0094x over previous
; template <bool RWKV> __device__ __forceinline__ void scan_load_finish(LAS unsigned char* buf, const ScanLd& L, int lt) {
;     const int lw = lt >> 6, lane = lt & 63, sl = lane >> 2, col = 16 * lw + 4 * (lane & 3);
;     float d[4], c[4], k[4], r[4], v[4], kk[4], nb[4];
;     unpack4(L.rd, d); unpack4(L.rk, k); unpack4(L.rr, r); unpack4(L.rv, v); unpack4(L.rkk, kk); unpack4(L.rnb, nb);
; #pragma unroll
;     for (int i = 0; i < 4; ++i) c[i] = d[i];
; #pragma unroll
;     for (int dl = 4; dl < 64; dl <<= 1)
; #pragma unroll
;         for (int i = 0; i < 4; ++i) { const float t = __shfl_up(c[i], dl); c[i] += (lane >= dl) ? t : 0.f; }
;     float o1[4], o2[4], o3[4], o4[4]; f32x4 we;
; #pragma unroll
;     for (int i = 0; i < 4; ++i) { const float W = __expf(-c[i]), iW = __expf(c[i]), Wp = __expf(d[i] - c[i]); o1[i] = RWKV ? kk[i] * Wp : 0.f; o2[i] = RWKV ? nb[i] * iW : 0.f; o3[i] = k[i] * iW; o4[i] = r[i] * W; we[i] = W; }
;     u32x2 w;
;     w.x = cvt2(o1[0], o1[1]); w.y = cvt2(o1[2], o1[3]); *(LAS u32x2*)(buf + SB_XA + sl * 144 + col * 2) = w;
;     w.x = cvt2(o4[0], o4[1]); w.y = cvt2(o4[2], o4[3]); *(LAS u32x2*)(buf + SB_XA + (16 + sl) * 144 + col * 2) = w;
;     w.x = cvt2(o2[0], o2[1]); w.y = cvt2(o2[2], o2[3]); *(LAS u32x2*)(buf + SB_XB + sl * 144 + col * 2) = w;
;     w.x = cvt2(o3[0], o3[1]); w.y = cvt2(o3[2], o3[3]); *(LAS u32x2*)(buf + SB_XB + (16 + sl) * 144 + col * 2) = w;
; #pragma unroll
;     for (int i = 0; i < 4; ++i) {
;         *(LAS unsigned short*)(buf + SB_XBT + (col + i) * 80 + sl * 2) = (unsigned short)(cvt2(o2[i], 0.f) & 0xffffu);
;         *(LAS unsigned short*)(buf + SB_XBT + (col + i) * 80 + (16 + sl) * 2) = (unsigned short)(cvt2(o3[i], 0.f) & 0xffffu);
;         *(LAS unsigned short*)(buf + SB_VT + (col + i) * 48 + sl * 2) = (unsigned short)(cvt2(v[i], 0.f) & 0xffffu); }
;     if (sl == SC_CH - 1) *(LAS f32x4*)(buf + SB_WE + col * 4) = we;
; }
; template <bool RWKV> __device__ __forceinline__ void scan_item(LAS unsigned char* lds, const ScanSrc& S, int wid, int lane) {
;     ...
;         if (is_ld) {
;             if (c + 3 < NCH) scan_load_finish<RWKV>(lds + ((b0 + 3) & 3) * SC_BUF, L, lt);
;             if (c + 4 < NCH) scan_load_issue<RWKV>(L, S, c + 4, lt); }
;         else if (is_prep) { if (c + 2 < NCH) scan_prep_m1<RWKV>(lds + ((b0 + 2) & 3) * SC_BUF, lds + SC_IMG + i2 * SW_SIZE, lane); }
.LBB0_640:
	s_cmpk_gt_u32 s69, 0xf8
	s_cbranch_scc1 .Lrw_ld_shared
	s_bitcmp1_b32 s69, 0
	s_cbranch_scc1 .Lrw_ld_shared
.Lrw_fl_even:
	s_add_i32 s0, s70, -1
	s_and_b32 s0, s0, 3
	s_mulk_i32 s0, 0x4500
	v_add_u32_e32 v190, s0, v250
	s_waitcnt vmcnt(6)
	v_lshlrev_b32_e32 v32, 16, v76
	v_and_b32_e32 v33, 0xffff0000, v76
	v_lshlrev_b32_e32 v34, 16, v77
	v_and_b32_e32 v35, 0xffff0000, v77
	v_mul_f32_e32 v52, 0x3fb8aa3b, v32
	v_mul_f32_e32 v53, 0x3fb8aa3b, v33
	v_mul_f32_e32 v54, 0x3fb8aa3b, v34
	v_mul_f32_e32 v55, 0x3fb8aa3b, v35
	v_add_f32_dpp v52, v52, v52 row_shr:4 row_mask:0xf bank_mask:0xf
	v_add_f32_dpp v53, v53, v53 row_shr:4 row_mask:0xf bank_mask:0xf
	v_add_f32_dpp v54, v54, v54 row_shr:4 row_mask:0xf bank_mask:0xf
	v_add_f32_dpp v55, v55, v55 row_shr:4 row_mask:0xf bank_mask:0xf
	v_add_f32_dpp v52, v52, v52 row_shr:8 row_mask:0xf bank_mask:0xf
	v_add_f32_dpp v53, v53, v53 row_shr:8 row_mask:0xf bank_mask:0xf
	v_add_f32_dpp v54, v54, v54 row_shr:8 row_mask:0xf bank_mask:0xf
	v_add_f32_dpp v55, v55, v55 row_shr:8 row_mask:0xf bank_mask:0xf
	ds_bpermute_b32 v60, v251, v52
	ds_bpermute_b32 v61, v251, v53
	ds_bpermute_b32 v62, v251, v54
	ds_bpermute_b32 v63, v251, v55
	ds_write_b16 v190, v82 offset:14336
	ds_write_b16_d16_hi v190, v82 offset:14384
	ds_write_b16 v190, v83 offset:14432
	ds_write_b16_d16_hi v190, v83 offset:14480
	v_lshlrev_b32_e32 v36, 16, v78
	v_and_b32_e32 v37, 0xffff0000, v78
	v_lshlrev_b32_e32 v38, 16, v79
	v_and_b32_e32 v39, 0xffff0000, v79
	v_lshlrev_b32_e32 v40, 16, v80
	v_and_b32_e32 v41, 0xffff0000, v80
	v_lshlrev_b32_e32 v42, 16, v81
	v_and_b32_e32 v43, 0xffff0000, v81
	v_lshlrev_b32_e32 v44, 16, v84
	v_and_b32_e32 v45, 0xffff0000, v84
	v_lshlrev_b32_e32 v46, 16, v85
	v_and_b32_e32 v47, 0xffff0000, v85
	v_lshlrev_b32_e32 v48, 16, v86
	v_and_b32_e32 v49, 0xffff0000, v86
	v_lshlrev_b32_e32 v50, 16, v87
	v_and_b32_e32 v51, 0xffff0000, v87
	s_waitcnt lgkmcnt(4)
	v_fmac_f32_e32 v52, v60, v253
	v_fmac_f32_e32 v53, v61, v253
	v_fmac_f32_e32 v54, v62, v253
	v_fmac_f32_e32 v55, v63, v253
	ds_bpermute_b32 v60, v252, v52
	ds_bpermute_b32 v61, v252, v53
	ds_bpermute_b32 v62, v252, v54
	ds_bpermute_b32 v63, v252, v55
	global_load_dwordx2 v[76:77], v[234:235], off
	global_load_dwordx2 v[78:79], v[236:237], off
	global_load_dwordx2 v[80:81], v[238:239], off
	global_load_dwordx2 v[82:83], v[240:241], off
	global_load_dwordx2 v[84:85], v[242:243], off
	global_load_dwordx2 v[86:87], v[246:247], off
	v_lshl_add_u64 v[234:235], v[234:235], 0, s[98:99]
	v_lshl_add_u64 v[236:237], v[236:237], 0, s[100:101]
	v_lshl_add_u64 v[238:239], v[238:239], 0, s[100:101]
	v_lshl_add_u64 v[240:241], v[240:241], 0, s[100:101]
	v_lshl_add_u64 v[242:243], v[242:243], 0, s[98:99]
	v_lshl_add_u64 v[246:247], v[246:247], 0, s[98:99]
	s_waitcnt lgkmcnt(0)
	v_fmac_f32_e32 v52, v60, v245
	v_fmac_f32_e32 v53, v61, v245
	v_fmac_f32_e32 v54, v62, v245
	v_fmac_f32_e32 v55, v63, v245
	v_fmamk_f32 v56, v32, 0xbfb8aa3b, v52
	v_fmamk_f32 v57, v33, 0xbfb8aa3b, v53
	v_fmamk_f32 v58, v34, 0xbfb8aa3b, v54
	v_fmamk_f32 v59, v35, 0xbfb8aa3b, v55
	v_exp_f32_e64 v64, -v52
	v_exp_f32_e64 v65, -v53
	v_exp_f32_e64 v66, -v54
	v_exp_f32_e64 v67, -v55
	v_exp_f32_e32 v68, v52
	v_exp_f32_e32 v69, v53
	v_exp_f32_e32 v70, v54
	v_exp_f32_e32 v71, v55
	v_exp_f32_e64 v192, -v56
	v_exp_f32_e64 v193, -v57
	v_exp_f32_e64 v194, -v58
	v_exp_f32_e64 v195, -v59
	v_add_u32_e32 v191, s0, v248
	v_pk_mul_f32 v[208:209], v[64:65], v[40:41]
	v_pk_mul_f32 v[210:211], v[66:67], v[42:43]
	v_pk_mul_f32 v[200:201], v[68:69], v[48:49]
	v_pk_mul_f32 v[202:203], v[70:71], v[50:51]
	v_pk_mul_f32 v[204:205], v[68:69], v[36:37]
	v_pk_mul_f32 v[206:207], v[70:71], v[38:39]
	v_pk_mul_f32 v[196:197], v[192:193], v[44:45]
	v_pk_mul_f32 v[198:199], v[194:195], v[46:47]
	v_cvt_pk_bf16_f32 v218, v208, v209
	v_cvt_pk_bf16_f32 v219, v210, v211
	v_cvt_pk_bf16_f32 v214, v200, v201
	v_cvt_pk_bf16_f32 v215, v202, v203
	v_cvt_pk_bf16_f32 v216, v204, v205
	v_cvt_pk_bf16_f32 v217, v206, v207
	v_cvt_pk_bf16_f32 v212, v196, v197
	v_cvt_pk_bf16_f32 v213, v198, v199
	v_add_u32_e32 v220, 0x900, v191
	v_add_u32_e32 v221, s0, v249
	ds_write2st64_b64 v220, v[218:219], v[216:217] offset1:9
	ds_write2st64_b64 v191, v[212:213], v[214:215] offset1:9
	ds_write_b16 v221, v214 offset:9216
	ds_write_b16_d16_hi v221, v214 offset:9296
	ds_write_b16 v221, v215 offset:9376
	ds_write_b16_d16_hi v221, v215 offset:9456
	ds_write_b16 v221, v216 offset:9248
	ds_write_b16_d16_hi v221, v216 offset:9328
	ds_write_b16 v221, v217 offset:9408
	ds_write_b16_d16_hi v221, v217 offset:9488
	s_and_saveexec_b64 s[42:43], s[14:15]
	v_add_u32_e32 v60, s0, v188
	ds_write_b128 v60, v[64:67] offset:17408
	s_or_b64 exec, exec, s[42:43]
	s_waitcnt lgkmcnt(0)
	s_barrier
; template <bool RWKV> __device__ __forceinline__ void scan_load_finish(LAS unsigned char* buf, const ScanLd& L, int lt) {
;     const int lw = lt >> 6, lane = lt & 63, sl = lane >> 2, col = 16 * lw + 4 * (lane & 3);
;     float d[4], c[4], k[4], r[4], v[4], kk[4], nb[4];
;     unpack4(L.rd, d); unpack4(L.rk, k); unpack4(L.rr, r); unpack4(L.rv, v); unpack4(L.rkk, kk); unpack4(L.rnb, nb);
; #pragma unroll
;     for (int i = 0; i < 4; ++i) c[i] = d[i];
; #pragma unroll
;     for (int dl = 4; dl < 64; dl <<= 1)
; #pragma unroll
;         for (int i = 0; i < 4; ++i) { const float t = __shfl_up(c[i], dl); c[i] += (lane >= dl) ? t : 0.f; }
;     float o1[4], o2[4], o3[4], o4[4]; f32x4 we;
; #pragma unroll
;     for (int i = 0; i < 4; ++i) { const float W = __expf(-c[i]), iW = __expf(c[i]), Wp = __expf(d[i] - c[i]); o1[i] = RWKV ? kk[i] * Wp : 0.f; o2[i] = RWKV ? nb[i] * iW : 0.f; o3[i] = k[i] * iW; o4[i] = r[i] * W; we[i] = W; }
;     u32x2 w;
;     w.x = cvt2(o1[0], o1[1]); w.y = cvt2(o1[2], o1[3]); *(LAS u32x2*)(buf + SB_XA + sl * 144 + col * 2) = w;
;     w.x = cvt2(o4[0], o4[1]); w.y = cvt2(o4[2], o4[3]); *(LAS u32x2*)(buf + SB_XA + (16 + sl) * 144 + col * 2) = w;
;     w.x = cvt2(o2[0], o2[1]); w.y = cvt2(o2[2], o2[3]); *(LAS u32x2*)(buf + SB_XB + sl * 144 + col * 2) = w;
;     w.x = cvt2(o3[0], o3[1]); w.y = cvt2(o3[2], o3[3]); *(LAS u32x2*)(buf + SB_XB + (16 + sl) * 144 + col * 2) = w;
; #pragma unroll
;     for (int i = 0; i < 4; ++i) {
;         *(LAS unsigned short*)(buf + SB_XBT + (col + i) * 80 + sl * 2) = (unsigned short)(cvt2(o2[i], 0.f) & 0xffffu);
;         *(LAS unsigned short*)(buf + SB_XBT + (col + i) * 80 + (16 + sl) * 2) = (unsigned short)(cvt2(o3[i], 0.f) & 0xffffu);
;         *(LAS unsigned short*)(buf + SB_VT + (col + i) * 48 + sl * 2) = (unsigned short)(cvt2(v[i], 0.f) & 0xffffu); }
;     if (sl == SC_CH - 1) *(LAS f32x4*)(buf + SB_WE + col * 4) = we;
; }
; template <bool RWKV> __device__ __forceinline__ void scan_item(LAS unsigned char* lds, const ScanSrc& S, int wid, int lane) {
;     ...
;     for (int c = 0; c < NCH; ++c) {
;         const int i1 = i0 == 2 ? 0 : i0 + 1, i2 = i1 == 2 ? 0 : i1 + 1;
;         if (is_ld) {
;             if (c + 3 < NCH) scan_load_finish<RWKV>(lds + ((b0 + 3) & 3) * SC_BUF, L, lt);
;             if (c + 4 < NCH) scan_load_issue<RWKV>(L, S, c + 4, lt); }
	s_add_i32 s0, s70, 1
	s_and_b32 s70, s0, 3
	s_add_i32 s69, s69, 1
	s_add_i32 s67, s67, 16
	s_add_i32 s68, s68, -16
	s_add_i32 s0, s70, -1
	s_and_b32 s0, s0, 3
	s_mulk_i32 s0, 0x4500
	v_add_u32_e32 v190, s0, v250
	s_waitcnt vmcnt(6)
	v_lshlrev_b32_e32 v32, 16, v222
	v_and_b32_e32 v33, 0xffff0000, v222
	v_lshlrev_b32_e32 v34, 16, v223
	v_and_b32_e32 v35, 0xffff0000, v223
	v_mul_f32_e32 v52, 0x3fb8aa3b, v32
	v_mul_f32_e32 v53, 0x3fb8aa3b, v33
	v_mul_f32_e32 v54, 0x3fb8aa3b, v34
	v_mul_f32_e32 v55, 0x3fb8aa3b, v35
	v_add_f32_dpp v52, v52, v52 row_shr:4 row_mask:0xf bank_mask:0xf
	v_add_f32_dpp v53, v53, v53 row_shr:4 row_mask:0xf bank_mask:0xf
	v_add_f32_dpp v54, v54, v54 row_shr:4 row_mask:0xf bank_mask:0xf
	v_add_f32_dpp v55, v55, v55 row_shr:4 row_mask:0xf bank_mask:0xf
	v_add_f32_dpp v52, v52, v52 row_shr:8 row_mask:0xf bank_mask:0xf
	v_add_f32_dpp v53, v53, v53 row_shr:8 row_mask:0xf bank_mask:0xf
	v_add_f32_dpp v54, v54, v54 row_shr:8 row_mask:0xf bank_mask:0xf
	v_add_f32_dpp v55, v55, v55 row_shr:8 row_mask:0xf bank_mask:0xf
	ds_bpermute_b32 v60, v251, v52
	ds_bpermute_b32 v61, v251, v53
	ds_bpermute_b32 v62, v251, v54
	ds_bpermute_b32 v63, v251, v55
	ds_write_b16 v190, v228 offset:14336
	ds_write_b16_d16_hi v190, v228 offset:14384
	ds_write_b16 v190, v229 offset:14432
	ds_write_b16_d16_hi v190, v229 offset:14480
	v_lshlrev_b32_e32 v36, 16, v224
	v_and_b32_e32 v37, 0xffff0000, v224
	v_lshlrev_b32_e32 v38, 16, v225
	v_and_b32_e32 v39, 0xffff0000, v225
	v_lshlrev_b32_e32 v40, 16, v226
	v_and_b32_e32 v41, 0xffff0000, v226
	v_lshlrev_b32_e32 v42, 16, v227
	v_and_b32_e32 v43, 0xffff0000, v227
	v_lshlrev_b32_e32 v44, 16, v230
	v_and_b32_e32 v45, 0xffff0000, v230
	v_lshlrev_b32_e32 v46, 16, v231
	v_and_b32_e32 v47, 0xffff0000, v231
	v_lshlrev_b32_e32 v48, 16, v232
	v_and_b32_e32 v49, 0xffff0000, v232
	v_lshlrev_b32_e32 v50, 16, v233
	v_and_b32_e32 v51, 0xffff0000, v233
	s_waitcnt lgkmcnt(4)
	v_fmac_f32_e32 v52, v60, v253
	v_fmac_f32_e32 v53, v61, v253
	v_fmac_f32_e32 v54, v62, v253
	v_fmac_f32_e32 v55, v63, v253
	ds_bpermute_b32 v60, v252, v52
	ds_bpermute_b32 v61, v252, v53
	ds_bpermute_b32 v62, v252, v54
	ds_bpermute_b32 v63, v252, v55
	global_load_dwordx2 v[222:223], v[234:235], off
	global_load_dwordx2 v[224:225], v[236:237], off
	global_load_dwordx2 v[226:227], v[238:239], off
	global_load_dwordx2 v[228:229], v[240:241], off
	global_load_dwordx2 v[230:231], v[242:243], off
	global_load_dwordx2 v[232:233], v[246:247], off
	v_lshl_add_u64 v[234:235], v[234:235], 0, s[98:99]
	v_lshl_add_u64 v[236:237], v[236:237], 0, s[100:101]
	v_lshl_add_u64 v[238:239], v[238:239], 0, s[100:101]
	v_lshl_add_u64 v[240:241], v[240:241], 0, s[100:101]
	v_lshl_add_u64 v[242:243], v[242:243], 0, s[98:99]
	v_lshl_add_u64 v[246:247], v[246:247], 0, s[98:99]
	s_waitcnt lgkmcnt(0)
	v_fmac_f32_e32 v52, v60, v245
	v_fmac_f32_e32 v53, v61, v245
	v_fmac_f32_e32 v54, v62, v245
	v_fmac_f32_e32 v55, v63, v245
	v_fmamk_f32 v56, v32, 0xbfb8aa3b, v52
	v_fmamk_f32 v57, v33, 0xbfb8aa3b, v53
	v_fmamk_f32 v58, v34, 0xbfb8aa3b, v54
	v_fmamk_f32 v59, v35, 0xbfb8aa3b, v55
	v_exp_f32_e64 v64, -v52
	v_exp_f32_e64 v65, -v53
	v_exp_f32_e64 v66, -v54
	v_exp_f32_e64 v67, -v55
	v_exp_f32_e32 v68, v52
	v_exp_f32_e32 v69, v53
	v_exp_f32_e32 v70, v54
	v_exp_f32_e32 v71, v55
	v_exp_f32_e64 v192, -v56
	v_exp_f32_e64 v193, -v57
	v_exp_f32_e64 v194, -v58
	v_exp_f32_e64 v195, -v59
	v_add_u32_e32 v191, s0, v248
	v_pk_mul_f32 v[208:209], v[64:65], v[40:41]
	v_pk_mul_f32 v[210:211], v[66:67], v[42:43]
	v_pk_mul_f32 v[200:201], v[68:69], v[48:49]
	v_pk_mul_f32 v[202:203], v[70:71], v[50:51]
	v_pk_mul_f32 v[204:205], v[68:69], v[36:37]
	v_pk_mul_f32 v[206:207], v[70:71], v[38:39]
	v_pk_mul_f32 v[196:197], v[192:193], v[44:45]
	v_pk_mul_f32 v[198:199], v[194:195], v[46:47]
	v_cvt_pk_bf16_f32 v218, v208, v209
	v_cvt_pk_bf16_f32 v219, v210, v211
	v_cvt_pk_bf16_f32 v214, v200, v201
	v_cvt_pk_bf16_f32 v215, v202, v203
	v_cvt_pk_bf16_f32 v216, v204, v205
	v_cvt_pk_bf16_f32 v217, v206, v207
	v_cvt_pk_bf16_f32 v212, v196, v197
	v_cvt_pk_bf16_f32 v213, v198, v199
	v_add_u32_e32 v220, 0x900, v191
	v_add_u32_e32 v221, s0, v249
	ds_write2st64_b64 v220, v[218:219], v[216:217] offset1:9
	ds_write2st64_b64 v191, v[212:213], v[214:215] offset1:9
	ds_write_b16 v221, v214 offset:9216
	ds_write_b16_d16_hi v221, v214 offset:9296
	ds_write_b16 v221, v215 offset:9376
	ds_write_b16_d16_hi v221, v215 offset:9456
	ds_write_b16 v221, v216 offset:9248
	ds_write_b16_d16_hi v221, v216 offset:9328
	ds_write_b16 v221, v217 offset:9408
	ds_write_b16_d16_hi v221, v217 offset:9488
	s_and_saveexec_b64 s[42:43], s[14:15]
	v_add_u32_e32 v60, s0, v188
	ds_write_b128 v60, v[64:67] offset:17408
	s_or_b64 exec, exec, s[42:43]
	s_waitcnt lgkmcnt(0)
	s_barrier
	s_add_i32 s0, s70, 1
	s_and_b32 s70, s0, 3
	s_add_i32 s69, s69, 1
	s_add_i32 s67, s67, 16
	s_add_i32 s68, s68, -16
	s_cmpk_gt_u32 s69, 0xf8
	s_cbranch_scc0 .Lrw_fl_even
	s_branch .LBB0_614
